# mLSTM chunk loop: X partial-sum LDS reads hoisted (31 per chunk), decay-factor bcum/liv reads hoisted before the QK loop, QK^T and state-update MFMA loops with double-buffered operands
# speedup vs baseline: 1.0127x; 1.0018x over previous
; #define MFMA32(a, b, c) __builtin_amdgcn_mfma_f32_32x32x16_bf16((a), (b), (c), 0, 0, 0)
; DI void mma_tile(f32x16& acc, const bf16_t* A, int lda, const bf16_t* Bt, int ldb, int K, int lane) {
;   const int r = lane & 31, h = lane >> 5;
;   const bf16_t* ap = A + r * lda + 8 * h; const bf16_t* bp = Bt + r * ldb + 8 * h;
; #pragma unroll 2
;   for (int k = 0; k < K; k += 16) acc = MFMA32(*(const bf16x8*)(ap + k), *(const bf16x8*)(bp + k), acc);
; DI void mlstm_item(const float* b_i, const float* b_f, const bf16_t* proj, const bf16_t* Hqk, bf16_t* mix, int item, LP unsigned char* lds3) {
;     ...
;     if (wave < 4) { const int si = wave & 1, ti = wave >> 1; f32x16 acc = zero16();
;       mma_tile(acc, K + si * 32 * 264, 264, Q + ti * 32 * 264, 264, 256, lane);
;       const int t = ti * 32 + r; const float bt = bcum[t], mct = mcomb[t]; float ds = 0.f;
; #pragma unroll
;       for (int gq = 0; gq < 4; ++gq) { float v4[4];
; #pragma unroll
;         for (int e = 0; e < 4; ++e) { const int s = si * 32 + 8 * gq + 4 * hh + e; const float dd = (s <= t) ? __expf(bt - bcum[s] + liv[s] - mct) : 0.f; v4[e] = acc[4 * gq + e] * dd; ds += v4[e]; }
.LBB0_166:
	s_or_saveexec_b64 s[4:5], s[4:5]
	v_ashrrev_i32_e32 v64, 2, v243
	v_and_b32_e32 v168, 31, v243
	v_ashrrev_i32_e32 v247, 5, v243
	v_lshlrev_b32_e32 v245, 1, v64
	s_xor_b64 exec, exec, s[4:5]
	s_cbranch_execz .LBB0_204
	v_mul_u32_u24_e32 v64, 0x108, v168
	v_lshlrev_b32_e32 v64, 1, v64
	s_waitcnt lgkmcnt(0)
	v_and_b32_e32 v65, -16, v245
	v_add3_u32 v80, v212, v64, v65
	v_add3_u32 v81, v65, v64, v236
	v_mov_b32_e32 v64, 0
	s_mov_b32 s16, -16
	v_mov_b32_e32 v65, v64
	v_mov_b32_e32 v66, v64
	v_mov_b32_e32 v67, v64
	v_mov_b32_e32 v68, v64
	v_mov_b32_e32 v69, v64
	v_mov_b32_e32 v70, v64
	v_mov_b32_e32 v71, v64
	v_mov_b32_e32 v72, v64
	v_mov_b32_e32 v73, v64
	v_mov_b32_e32 v74, v64
	v_mov_b32_e32 v75, v64
	v_mov_b32_e32 v76, v64
	v_mov_b32_e32 v77, v64
	v_mov_b32_e32 v78, v64
	v_mov_b32_e32 v79, v64
	v_lshl_add_u32 v135, v247, 2, v210
	v_lshl_add_u32 v135, v135, 2, 32
	v_add_u32_e32 v135, 0x1f800, v135
	ds_read_b32 v96, v135
	ds_read_b32 v97, v135 offset:4
	ds_read_b32 v98, v135 offset:8
	ds_read_b32 v99, v135 offset:12
	ds_read_b32 v100, v135 offset:32
	ds_read_b32 v101, v135 offset:36
	ds_read_b32 v102, v135 offset:40
	ds_read_b32 v103, v135 offset:44
	ds_read_b32 v104, v135 offset:64
	ds_read_b32 v105, v135 offset:68
	ds_read_b32 v106, v135 offset:72
	ds_read_b32 v107, v135 offset:76
	ds_read_b32 v108, v135 offset:96
	ds_read_b32 v109, v135 offset:100
	ds_read_b32 v110, v135 offset:104
	ds_read_b32 v111, v135 offset:108
	ds_read_b32 v112, v135 offset:256
	ds_read_b32 v113, v135 offset:260
	ds_read_b32 v114, v135 offset:264
	ds_read_b32 v115, v135 offset:268
	ds_read_b32 v116, v135 offset:288
	ds_read_b32 v117, v135 offset:292
	ds_read_b32 v118, v135 offset:296
	ds_read_b32 v119, v135 offset:300
	ds_read_b32 v120, v135 offset:320
	ds_read_b32 v121, v135 offset:324
	ds_read_b32 v122, v135 offset:328
	ds_read_b32 v123, v135 offset:332
	ds_read_b32 v124, v135 offset:352
	ds_read_b32 v125, v135 offset:356
	ds_read_b32 v126, v135 offset:360
	ds_read_b32 v127, v135 offset:364
	ds_read_b128 v[82:85], v81
	ds_read_b128 v[86:89], v80
.LBB0_168:
	ds_read_b128 v[128:131], v81 offset:32
	ds_read_b128 v[132:135], v80 offset:32
	s_add_i32 s16, s16, 32
	v_add_u32_e32 v81, 64, v81
	v_add_u32_e32 v80, 64, v80
	s_waitcnt lgkmcnt(2)
	v_mfma_f32_32x32x16_bf16 v[64:79], v[82:85], v[86:89], v[64:79]
	s_cmpk_lt_u32 s16, 0xf0
	s_cbranch_scc0 .Lmlqk_last
	ds_read_b128 v[82:85], v81
	ds_read_b128 v[86:89], v80
	s_waitcnt lgkmcnt(2)
	v_mfma_f32_32x32x16_bf16 v[64:79], v[128:131], v[132:135], v[64:79]
	s_branch .LBB0_168
.Lmlqk_last:
	s_waitcnt lgkmcnt(0)
	v_mfma_f32_32x32x16_bf16 v[64:79], v[128:131], v[132:135], v[64:79]
	v_or_b32_e32 v80, v168, v211
	v_lshl_add_u32 v81, v80, 2, 32
	v_add_u32_e32 v82, 0x1f800, v81
	v_add_u32_e32 v81, 0x1fa00, v81
	ds_read_b32 v82, v82
	ds_read_b32 v81, v81
	v_lshl_add_u32 v83, v247, 2, v210
	v_cmp_le_i32_e32 vcc, v83, v80
	v_mov_b32_e32 v85, 0
	v_lshl_add_u32 v86, v83, 2, 32
	v_mov_b32_e32 v84, 0
	s_and_saveexec_b64 s[16:17], vcc
	s_cbranch_execz .LBB0_171
	v_add_u32_e32 v84, 0x1f800, v86
	v_add_u32_e32 v87, 0x1f900, v86
	s_waitcnt lgkmcnt(0)
	v_sub_f32_e32 v84, v82, v96
	v_add_f32_e32 v84, v84, v112
	v_sub_f32_e32 v84, v84, v81
	v_mul_f32_e32 v84, 0x3fb8aa3b, v84
	v_exp_f32_e32 v84, v84
.LBB0_171:
	s_or_b64 exec, exec, s[16:17]
	v_cmp_lt_i32_e32 vcc, v83, v80
	s_and_saveexec_b64 s[16:17], vcc
	s_cbranch_execz .LBB0_173
	v_add_u32_e32 v85, 0x1f804, v86
	v_add_u32_e32 v86, 0x1f904, v86
	v_sub_f32_e32 v85, v82, v97
	v_add_f32_e32 v85, v85, v113
	v_sub_f32_e32 v85, v85, v81
	v_mul_f32_e32 v85, 0x3fb8aa3b, v85
	v_exp_f32_e32 v85, v85
.LBB0_173:
	s_or_b64 exec, exec, s[16:17]
	v_or_b32_e32 v88, 2, v83
	v_cmp_le_i32_e32 vcc, v88, v80
	v_mov_b32_e32 v86, 0
	v_mov_b32_e32 v87, 0
	s_and_saveexec_b64 s[16:17], vcc
	s_cbranch_execz .LBB0_175
	v_lshl_add_u32 v87, v88, 2, 32
	v_add_u32_e32 v88, 0x1f800, v87
	v_add_u32_e32 v87, 0x1f900, v87
	v_sub_f32_e32 v88, v82, v98
	v_add_f32_e32 v87, v88, v114
	v_sub_f32_e32 v87, v87, v81
	v_mul_f32_e32 v87, 0x3fb8aa3b, v87
	v_exp_f32_e32 v87, v87
.LBB0_175:
	s_or_b64 exec, exec, s[16:17]
	v_or_b32_e32 v88, 3, v83
	v_cmp_le_i32_e32 vcc, v88, v80
	s_and_saveexec_b64 s[16:17], vcc
	s_cbranch_execz .LBB0_177
	v_lshl_add_u32 v86, v88, 2, 32
	v_add_u32_e32 v88, 0x1f800, v86
	v_add_u32_e32 v86, 0x1f900, v86
	v_sub_f32_e32 v88, v82, v99
	v_add_f32_e32 v86, v88, v115
	v_sub_f32_e32 v86, v86, v81
	v_mul_f32_e32 v86, 0x3fb8aa3b, v86
	v_exp_f32_e32 v86, v86
.LBB0_177:
	s_or_b64 exec, exec, s[16:17]
	s_movk_i32 s16, 0x90
	v_mul_f32_e32 v84, v64, v84
	v_mul_f32_e32 v65, v65, v85
	v_mul_f32_e32 v66, v66, v87
	v_mad_u64_u32 v[88:89], s[16:17], v80, s16, v[184:185]
	v_lshlrev_b32_e32 v64, 3, v247
	v_mul_f32_e32 v67, v67, v86
	v_cvt_pk_bf16_f32 v86, v84, v65
	v_cvt_pk_bf16_f32 v87, v66, v67
	v_add_u32_e32 v64, v88, v64
	ds_write_b64 v64, v[86:87] offset:33792
	v_add_u32_e32 v87, 8, v83
	v_cmp_le_i32_e32 vcc, v87, v80
	v_mov_b32_e32 v85, 0
	v_mov_b32_e32 v86, 0
	s_and_saveexec_b64 s[16:17], vcc
	s_cbranch_execz .LBB0_179
	v_lshl_add_u32 v86, v87, 2, 32
	v_add_u32_e32 v87, 0x1f800, v86
	v_add_u32_e32 v86, 0x1f900, v86
	v_sub_f32_e32 v87, v82, v100
	v_add_f32_e32 v86, v87, v116
	v_sub_f32_e32 v86, v86, v81
	v_mul_f32_e32 v86, 0x3fb8aa3b, v86
	v_exp_f32_e32 v86, v86
; DI unsigned pk2(float a, float b) { const f32x2_t f = {a, b}; const bf16x2_t r = __builtin_convertvector(f, bf16x2_t); return __builtin_bit_cast(unsigned, r); }
; DI void mlstm_item(const float* b_i, const float* b_f, const bf16_t* proj, const bf16_t* Hqk, bf16_t* mix, int item, LP unsigned char* lds3) {
;     ...
;       for (int gq = 0; gq < 4; ++gq) { float v4[4];
; #pragma unroll
;         for (int e = 0; e < 4; ++e) { const int s = si * 32 + 8 * gq + 4 * hh + e; const float dd = (s <= t) ? __expf(bt - bcum[s] + liv[s] - mct) : 0.f; v4[e] = acc[4 * gq + e] * dd; ds += v4[e]; }
;         u32x2 w; w.x = pk2(v4[0], v4[1]); w.y = pk2(v4[2], v4[3]); *(u32x2*)(Sm + t * 72 + si * 32 + 8 * gq + 4 * hh) = w; }
.LBB0_179:
	s_or_b64 exec, exec, s[16:17]
	v_add_u32_e32 v87, 9, v83
	v_cmp_le_i32_e32 vcc, v87, v80
	s_and_saveexec_b64 s[16:17], vcc
	s_cbranch_execz .LBB0_181
	v_lshl_add_u32 v85, v87, 2, 32
	v_add_u32_e32 v87, 0x1f800, v85
	v_add_u32_e32 v85, 0x1f900, v85
	v_sub_f32_e32 v87, v82, v101
	v_add_f32_e32 v85, v87, v117
	v_sub_f32_e32 v85, v85, v81
	v_mul_f32_e32 v85, 0x3fb8aa3b, v85
	v_exp_f32_e32 v85, v85
.LBB0_181:
	s_or_b64 exec, exec, s[16:17]
	v_add_u32_e32 v89, 10, v83
	v_cmp_le_i32_e32 vcc, v89, v80
	v_mov_b32_e32 v87, 0
	v_mov_b32_e32 v88, 0
	s_and_saveexec_b64 s[16:17], vcc
	s_cbranch_execz .LBB0_183
	v_lshl_add_u32 v88, v89, 2, 32
	v_add_u32_e32 v89, 0x1f800, v88
	v_add_u32_e32 v88, 0x1f900, v88
	v_sub_f32_e32 v89, v82, v102
	v_add_f32_e32 v88, v89, v118
	v_sub_f32_e32 v88, v88, v81
	v_mul_f32_e32 v88, 0x3fb8aa3b, v88
	v_exp_f32_e32 v88, v88
.LBB0_183:
	s_or_b64 exec, exec, s[16:17]
	v_add_u32_e32 v89, 11, v83
	v_cmp_le_i32_e32 vcc, v89, v80
	s_and_saveexec_b64 s[16:17], vcc
	s_cbranch_execz .LBB0_185
	v_lshl_add_u32 v87, v89, 2, 32
	v_add_u32_e32 v89, 0x1f800, v87
	v_add_u32_e32 v87, 0x1f900, v87
	v_sub_f32_e32 v89, v82, v103
	v_add_f32_e32 v87, v89, v119
	v_sub_f32_e32 v87, v87, v81
	v_mul_f32_e32 v87, 0x3fb8aa3b, v87
	v_exp_f32_e32 v87, v87
.LBB0_185:
	s_or_b64 exec, exec, s[16:17]
	v_mul_f32_e32 v68, v68, v86
	v_mul_f32_e32 v69, v69, v85
	v_mul_f32_e32 v70, v70, v88
	v_mul_f32_e32 v71, v71, v87
	v_cvt_pk_bf16_f32 v86, v68, v69
	v_cvt_pk_bf16_f32 v87, v70, v71
	ds_write_b64 v64, v[86:87] offset:33808
	v_add_u32_e32 v87, 16, v83
	v_cmp_le_i32_e32 vcc, v87, v80
	v_mov_b32_e32 v85, 0
	v_mov_b32_e32 v86, 0
	s_and_saveexec_b64 s[16:17], vcc
	s_cbranch_execz .LBB0_187
	v_lshl_add_u32 v86, v87, 2, 32
	v_add_u32_e32 v87, 0x1f800, v86
	v_add_u32_e32 v86, 0x1f900, v86
	v_sub_f32_e32 v87, v82, v104
	v_add_f32_e32 v86, v87, v120
	v_sub_f32_e32 v86, v86, v81
	v_mul_f32_e32 v86, 0x3fb8aa3b, v86
	v_exp_f32_e32 v86, v86
.LBB0_187:
	s_or_b64 exec, exec, s[16:17]
	v_add_u32_e32 v87, 17, v83
	v_cmp_le_i32_e32 vcc, v87, v80
	s_and_saveexec_b64 s[16:17], vcc
	s_cbranch_execz .LBB0_189
	v_lshl_add_u32 v85, v87, 2, 32
	v_add_u32_e32 v87, 0x1f800, v85
	v_add_u32_e32 v85, 0x1f900, v85
	v_sub_f32_e32 v87, v82, v105
	v_add_f32_e32 v85, v87, v121
	v_sub_f32_e32 v85, v85, v81
	v_mul_f32_e32 v85, 0x3fb8aa3b, v85
	v_exp_f32_e32 v85, v85
.LBB0_189:
	s_or_b64 exec, exec, s[16:17]
	v_add_u32_e32 v89, 18, v83
	v_cmp_le_i32_e32 vcc, v89, v80
	v_mov_b32_e32 v87, 0
	v_mov_b32_e32 v88, 0
	s_and_saveexec_b64 s[16:17], vcc
	s_cbranch_execz .LBB0_191
	v_lshl_add_u32 v88, v89, 2, 32
	v_add_u32_e32 v89, 0x1f800, v88
	v_add_u32_e32 v88, 0x1f900, v88
	v_sub_f32_e32 v89, v82, v106
	v_add_f32_e32 v88, v89, v122
	v_sub_f32_e32 v88, v88, v81
	v_mul_f32_e32 v88, 0x3fb8aa3b, v88
	v_exp_f32_e32 v88, v88
.LBB0_191:
	s_or_b64 exec, exec, s[16:17]
	v_add_u32_e32 v89, 19, v83
	v_cmp_le_i32_e32 vcc, v89, v80
	s_and_saveexec_b64 s[16:17], vcc
	s_cbranch_execz .LBB0_193
	v_lshl_add_u32 v87, v89, 2, 32
	v_add_u32_e32 v89, 0x1f800, v87
	v_add_u32_e32 v87, 0x1f900, v87
	v_sub_f32_e32 v89, v82, v107
	v_add_f32_e32 v87, v89, v123
	v_sub_f32_e32 v87, v87, v81
	v_mul_f32_e32 v87, 0x3fb8aa3b, v87
	v_exp_f32_e32 v87, v87
.LBB0_193:
	s_or_b64 exec, exec, s[16:17]
	v_mul_f32_e32 v72, v72, v86
	v_mul_f32_e32 v73, v73, v85
	v_mul_f32_e32 v74, v74, v88
	v_mul_f32_e32 v75, v75, v87
	v_cvt_pk_bf16_f32 v86, v72, v73
	v_cvt_pk_bf16_f32 v87, v74, v75
	ds_write_b64 v64, v[86:87] offset:33824
	v_add_u32_e32 v87, 24, v83
	v_cmp_le_i32_e32 vcc, v87, v80
	v_mov_b32_e32 v85, 0
	v_mov_b32_e32 v86, 0
	s_and_saveexec_b64 s[16:17], vcc
	s_cbranch_execz .LBB0_195
	v_lshl_add_u32 v86, v87, 2, 32
	v_add_u32_e32 v87, 0x1f800, v86
	v_add_u32_e32 v86, 0x1f900, v86
	v_sub_f32_e32 v87, v82, v108
	v_add_f32_e32 v86, v87, v124
	v_sub_f32_e32 v86, v86, v81
	v_mul_f32_e32 v86, 0x3fb8aa3b, v86
	v_exp_f32_e32 v86, v86
.LBB0_195:
	s_or_b64 exec, exec, s[16:17]
	v_add_u32_e32 v87, 25, v83
	v_cmp_le_i32_e32 vcc, v87, v80
	s_and_saveexec_b64 s[16:17], vcc
	s_cbranch_execz .LBB0_197
	v_lshl_add_u32 v85, v87, 2, 32
	v_add_u32_e32 v87, 0x1f800, v85
	v_add_u32_e32 v85, 0x1f900, v85
	v_sub_f32_e32 v87, v82, v109
	v_add_f32_e32 v85, v87, v125
	v_sub_f32_e32 v85, v85, v81
	v_mul_f32_e32 v85, 0x3fb8aa3b, v85
	v_exp_f32_e32 v85, v85
.LBB0_197:
	s_or_b64 exec, exec, s[16:17]
	v_add_u32_e32 v89, 26, v83
	v_cmp_le_i32_e32 vcc, v89, v80
	v_mov_b32_e32 v87, 0
	v_mov_b32_e32 v88, 0
	s_and_saveexec_b64 s[16:17], vcc
	s_cbranch_execz .LBB0_199
	v_lshl_add_u32 v88, v89, 2, 32
	v_add_u32_e32 v89, 0x1f800, v88
	v_add_u32_e32 v88, 0x1f900, v88
	v_sub_f32_e32 v89, v82, v110
	v_add_f32_e32 v88, v89, v126
	v_sub_f32_e32 v88, v88, v81
	v_mul_f32_e32 v88, 0x3fb8aa3b, v88
	v_exp_f32_e32 v88, v88
.LBB0_199:
	s_or_b64 exec, exec, s[16:17]
	v_add_u32_e32 v83, 27, v83
	v_cmp_le_i32_e32 vcc, v83, v80
	s_and_saveexec_b64 s[16:17], vcc
	s_cbranch_execz .LBB0_201
	v_lshl_add_u32 v83, v83, 2, 32
	v_add_u32_e32 v87, 0x1f800, v83
	v_add_u32_e32 v83, 0x1f900, v83
	v_sub_f32_e32 v82, v82, v111
	v_add_f32_e32 v82, v82, v127
	v_sub_f32_e32 v81, v82, v81
	v_mul_f32_e32 v81, 0x3fb8aa3b, v81
	v_exp_f32_e32 v87, v81

; DI int crow(int reg, int h) { return (reg & 3) + 8 * (reg >> 2) + 4 * h; }
; DI void mlstm_item(const float* b_i, const float* b_f, const bf16_t* proj, const bf16_t* Hqk, bf16_t* mix, int item, LP unsigned char* lds3) {
;     ...
;     if (dh == 0) {
; #pragma unroll
;       for (int ti = 0; ti < 2; ++ti)
; #pragma unroll
;         for (int i = 0; i < 16; ++i) { const int t = ti * 32 + crow(i, hh);
;           mix[(tok0 + t) * 2048 + h * 512 + vq * 128 + vi * 32 + r] = f2bf((acc[ti][i] + X[t * 128 + vi * 32 + r]) * qn[t]); }
.LBB0_220:
	s_andn2_saveexec_b64 s[18:19], s[4:5]
	s_cbranch_execz .LBB0_222
	v_lshl_add_u32 v140, v168, 2, v223
	v_add_u32_e32 v136, v140, v248
	ds_read_b32 v136, v136
	v_lshlrev_b32_e32 v138, 2, v247
	v_lshl_add_u32 v128, v138, 9, v140
	ds_read_b32 v96, v128 offset:512
	ds_read_b32 v97, v128 offset:1024
	ds_read_b32 v98, v128 offset:1536
	ds_read_b32 v99, v128 offset:4096
	ds_read_b32 v100, v128 offset:4608
	ds_read_b32 v101, v128 offset:5120
	ds_read_b32 v102, v128 offset:5632
	ds_read_b32 v103, v128 offset:8192
	ds_read_b32 v104, v128 offset:8704
	ds_read_b32 v105, v128 offset:9216
	ds_read_b32 v106, v128 offset:9728
	ds_read_b32 v107, v128 offset:12288
	ds_read_b32 v108, v128 offset:12800
	ds_read_b32 v109, v128 offset:13312
	ds_read_b32 v110, v128 offset:13824
	ds_read_b32 v111, v128 offset:16384
	ds_read_b32 v112, v128 offset:16896
	ds_read_b32 v113, v128 offset:17408
	ds_read_b32 v114, v128 offset:17920
	ds_read_b32 v115, v128 offset:20480
	ds_read_b32 v116, v128 offset:20992
	ds_read_b32 v117, v128 offset:21504
	ds_read_b32 v118, v128 offset:22016
	ds_read_b32 v119, v128 offset:24576
	ds_read_b32 v120, v128 offset:25088
	ds_read_b32 v121, v128 offset:25600
	ds_read_b32 v122, v128 offset:26112
	ds_read_b32 v123, v128 offset:28672
	ds_read_b32 v124, v128 offset:29184
	ds_read_b32 v125, v128 offset:29696
	ds_read_b32 v126, v128 offset:30208
	v_ashrrev_i32_e32 v139, 31, v138
	v_or_b32_e32 v168, v168, v222
	s_waitcnt lgkmcnt(0)
	v_add_f32_e32 v136, v80, v136
	v_lshl_add_u32 v80, v247, 4, 32
	v_add_u32_e32 v80, 0x1ff00, v80
	ds_read_b128 v[142:145], v80
	ds_read_b128 v[146:149], v80 offset:32
	s_waitcnt lgkmcnt(1)
	v_mul_f32_e32 v136, v136, v142
	v_cvt_pk_bf16_f32 v141, v136, s0
	v_lshl_add_u64 v[136:137], s[16:17], 0, v[138:139]
	v_lshlrev_b64 v[136:137], 12, v[136:137]
	v_lshl_add_u64 v[150:151], s[26:27], 0, v[136:137]
	v_lshlrev_b64 v[136:137], 1, v[168:169]
	v_lshl_add_u64 v[150:151], v[150:151], 0, v[136:137]
	global_store_short v[150:151], v141, off
	v_or_b32_e32 v150, 1, v138
	v_ashrrev_i32_e32 v151, 31, v150
	s_waitcnt lgkmcnt(0)
	v_add_f32_e32 v81, v81, v96
	v_mul_f32_e32 v81, v81, v143
	v_lshl_add_u64 v[142:143], s[16:17], 0, v[150:151]
	v_lshlrev_b64 v[142:143], 12, v[142:143]
	v_lshl_add_u64 v[142:143], s[26:27], 0, v[142:143]
	v_cvt_pk_bf16_f32 v81, v81, s0
	v_lshl_add_u64 v[142:143], v[142:143], 0, v[136:137]
	global_store_short v[142:143], v81, off
	v_or_b32_e32 v142, 2, v138
	v_ashrrev_i32_e32 v143, 31, v142
	v_lshl_add_u64 v[142:143], s[16:17], 0, v[142:143]
	v_lshlrev_b64 v[142:143], 12, v[142:143]
	v_lshl_add_u64 v[142:143], s[26:27], 0, v[142:143]
	s_waitcnt lgkmcnt(0)
	v_add_f32_e32 v81, v82, v97
	v_mul_f32_e32 v81, v81, v144
	v_cvt_pk_bf16_f32 v81, v81, s0
	v_lshl_add_u64 v[142:143], v[142:143], 0, v[136:137]
	v_or_b32_e32 v82, 3, v138
	global_store_short v[142:143], v81, off
	s_waitcnt lgkmcnt(0)
	v_add_f32_e32 v81, v83, v98
	v_ashrrev_i32_e32 v83, 31, v82
	v_lshl_add_u64 v[82:83], s[16:17], 0, v[82:83]
	v_lshlrev_b64 v[82:83], 12, v[82:83]
	v_mul_f32_e32 v81, v81, v145
	v_lshl_add_u64 v[82:83], s[26:27], 0, v[82:83]
	v_cvt_pk_bf16_f32 v81, v81, s0
	v_lshl_add_u64 v[82:83], v[82:83], 0, v[136:137]
	global_store_short v[82:83], v81, off
	v_add_u32_e32 v82, 8, v138
	v_ashrrev_i32_e32 v83, 31, v82
	v_lshl_add_u64 v[82:83], s[16:17], 0, v[82:83]
	v_lshlrev_b64 v[82:83], 12, v[82:83]
	v_lshl_add_u64 v[82:83], s[26:27], 0, v[82:83]
	s_waitcnt lgkmcnt(0)
	v_add_f32_e32 v81, v84, v99
	v_mul_f32_e32 v81, v81, v146
	v_cvt_pk_bf16_f32 v81, v81, s0
	v_lshl_add_u64 v[82:83], v[82:83], 0, v[136:137]
	global_store_short v[82:83], v81, off
	v_add_u32_e32 v82, 9, v138
	v_ashrrev_i32_e32 v83, 31, v82
	v_lshl_add_u64 v[82:83], s[16:17], 0, v[82:83]
	v_lshlrev_b64 v[82:83], 12, v[82:83]
	v_lshl_add_u64 v[82:83], s[26:27], 0, v[82:83]
	s_waitcnt lgkmcnt(0)
	v_add_f32_e32 v81, v85, v100
	v_mul_f32_e32 v81, v81, v147
	v_cvt_pk_bf16_f32 v81, v81, s0
	v_lshl_add_u64 v[82:83], v[82:83], 0, v[136:137]
	global_store_short v[82:83], v81, off
	v_add_u32_e32 v82, 10, v138
	v_ashrrev_i32_e32 v83, 31, v82
	v_lshl_add_u64 v[82:83], s[16:17], 0, v[82:83]
	v_lshlrev_b64 v[82:83], 12, v[82:83]
	v_lshl_add_u64 v[82:83], s[26:27], 0, v[82:83]
	s_waitcnt lgkmcnt(0)
	v_add_f32_e32 v81, v86, v101
	v_mul_f32_e32 v81, v81, v148
	v_cvt_pk_bf16_f32 v81, v81, s0
	v_lshl_add_u64 v[82:83], v[82:83], 0, v[136:137]
	global_store_short v[82:83], v81, off
	v_add_u32_e32 v82, 11, v138
	v_ashrrev_i32_e32 v83, 31, v82
	v_lshl_add_u64 v[82:83], s[16:17], 0, v[82:83]
	v_lshlrev_b64 v[82:83], 12, v[82:83]
	v_lshl_add_u64 v[82:83], s[26:27], 0, v[82:83]
	s_waitcnt lgkmcnt(0)
	v_add_f32_e32 v81, v87, v102
	v_mul_f32_e32 v81, v81, v149
	v_cvt_pk_bf16_f32 v81, v81, s0
	v_lshl_add_u64 v[82:83], v[82:83], 0, v[136:137]
	v_add_u32_e32 v86, 16, v138
	global_store_short v[82:83], v81, off
	ds_read_b128 v[82:85], v80 offset:64
	v_ashrrev_i32_e32 v87, 31, v86
	v_lshl_add_u64 v[86:87], s[16:17], 0, v[86:87]
	v_lshlrev_b64 v[86:87], 12, v[86:87]
	s_waitcnt lgkmcnt(1)
	v_add_f32_e32 v81, v88, v103
	s_waitcnt lgkmcnt(0)
	v_mul_f32_e32 v81, v81, v82
	v_lshl_add_u64 v[86:87], s[26:27], 0, v[86:87]
	v_cvt_pk_bf16_f32 v81, v81, s0
	v_lshl_add_u64 v[86:87], v[86:87], 0, v[136:137]
	global_store_short v[86:87], v81, off
	v_add_u32_e32 v86, 17, v138
	v_ashrrev_i32_e32 v87, 31, v86
	s_waitcnt lgkmcnt(0)
	v_add_f32_e32 v81, v89, v104
	v_mul_f32_e32 v81, v81, v83
	v_lshl_add_u64 v[82:83], s[16:17], 0, v[86:87]
	v_lshlrev_b64 v[82:83], 12, v[82:83]
	v_lshl_add_u64 v[82:83], s[26:27], 0, v[82:83]
	v_cvt_pk_bf16_f32 v81, v81, s0
	v_lshl_add_u64 v[82:83], v[82:83], 0, v[136:137]
	global_store_short v[82:83], v81, off
	v_add_u32_e32 v82, 18, v138
	v_ashrrev_i32_e32 v83, 31, v82
	v_lshl_add_u64 v[82:83], s[16:17], 0, v[82:83]
	v_lshlrev_b64 v[82:83], 12, v[82:83]
	v_lshl_add_u64 v[82:83], s[26:27], 0, v[82:83]
	s_waitcnt lgkmcnt(0)
; DI int crow(int reg, int h) { return (reg & 3) + 8 * (reg >> 2) + 4 * h; }
; DI void mlstm_item(const float* b_i, const float* b_f, const bf16_t* proj, const bf16_t* Hqk, bf16_t* mix, int item, LP unsigned char* lds3) {
;     ...
;         for (int i = 0; i < 16; ++i) { const int t = ti * 32 + crow(i, hh);
;           mix[(tok0 + t) * 2048 + h * 512 + vq * 128 + vi * 32 + r] = f2bf((acc[ti][i] + X[t * 128 + vi * 32 + r]) * qn[t]); }
	v_add_f32_e32 v81, v90, v105
	v_mul_f32_e32 v81, v81, v84
	v_cvt_pk_bf16_f32 v81, v81, s0
	v_lshl_add_u64 v[82:83], v[82:83], 0, v[136:137]
	global_store_short v[82:83], v81, off
	v_add_u32_e32 v82, 19, v138
	v_ashrrev_i32_e32 v83, 31, v82
	v_lshl_add_u64 v[82:83], s[16:17], 0, v[82:83]
	v_lshlrev_b64 v[82:83], 12, v[82:83]
	v_lshl_add_u64 v[82:83], s[26:27], 0, v[82:83]
	s_waitcnt lgkmcnt(0)
	v_add_f32_e32 v81, v91, v106
	v_mul_f32_e32 v81, v81, v85
	v_cvt_pk_bf16_f32 v81, v81, s0
	v_lshl_add_u64 v[82:83], v[82:83], 0, v[136:137]
	v_add_u32_e32 v86, 24, v138
	global_store_short v[82:83], v81, off
	ds_read_b128 v[82:85], v80 offset:96
	v_ashrrev_i32_e32 v87, 31, v86
	v_lshl_add_u64 v[86:87], s[16:17], 0, v[86:87]
	v_lshlrev_b64 v[86:87], 12, v[86:87]
	s_waitcnt lgkmcnt(1)
	v_add_f32_e32 v81, v92, v107
	s_waitcnt lgkmcnt(0)
	v_mul_f32_e32 v81, v81, v82
	v_lshl_add_u64 v[86:87], s[26:27], 0, v[86:87]
	v_cvt_pk_bf16_f32 v81, v81, s0
	v_lshl_add_u64 v[86:87], v[86:87], 0, v[136:137]
	global_store_short v[86:87], v81, off
	v_add_u32_e32 v86, 25, v138
	v_ashrrev_i32_e32 v87, 31, v86
	s_waitcnt lgkmcnt(0)
	v_add_f32_e32 v81, v93, v108
	v_mul_f32_e32 v81, v81, v83
	v_lshl_add_u64 v[82:83], s[16:17], 0, v[86:87]
	v_lshlrev_b64 v[82:83], 12, v[82:83]
	v_lshl_add_u64 v[82:83], s[26:27], 0, v[82:83]
	v_cvt_pk_bf16_f32 v81, v81, s0
	v_lshl_add_u64 v[82:83], v[82:83], 0, v[136:137]
	global_store_short v[82:83], v81, off
	v_add_u32_e32 v82, 26, v138
	v_ashrrev_i32_e32 v83, 31, v82
	v_lshl_add_u64 v[82:83], s[16:17], 0, v[82:83]
	v_lshlrev_b64 v[82:83], 12, v[82:83]
	v_lshl_add_u64 v[82:83], s[26:27], 0, v[82:83]
	s_waitcnt lgkmcnt(0)
	v_add_f32_e32 v81, v94, v109
	v_mul_f32_e32 v81, v81, v84
	v_cvt_pk_bf16_f32 v81, v81, s0
	v_lshl_add_u64 v[82:83], v[82:83], 0, v[136:137]
	global_store_short v[82:83], v81, off
	v_add_u32_e32 v82, 27, v138
	v_ashrrev_i32_e32 v83, 31, v82
	v_lshl_add_u64 v[82:83], s[16:17], 0, v[82:83]
	v_lshlrev_b64 v[82:83], 12, v[82:83]
	v_lshl_add_u64 v[82:83], s[26:27], 0, v[82:83]
	s_waitcnt lgkmcnt(0)
	v_add_f32_e32 v81, v95, v110
	v_mul_f32_e32 v81, v81, v85
	v_cvt_pk_bf16_f32 v81, v81, s0
	v_lshl_add_u64 v[82:83], v[82:83], 0, v[136:137]
	v_add_u32_e32 v86, 32, v138
	global_store_short v[82:83], v81, off
	ds_read_b128 v[82:85], v80 offset:128
	v_ashrrev_i32_e32 v87, 31, v86
	v_lshl_add_u64 v[86:87], s[16:17], 0, v[86:87]
	v_lshlrev_b64 v[86:87], 12, v[86:87]
	s_waitcnt lgkmcnt(1)
	v_add_f32_e32 v64, v64, v111
	s_waitcnt lgkmcnt(0)
	v_mul_f32_e32 v64, v64, v82
	v_lshl_add_u64 v[86:87], s[26:27], 0, v[86:87]
	v_cvt_pk_bf16_f32 v64, v64, s0
	v_lshl_add_u64 v[86:87], v[86:87], 0, v[136:137]
	global_store_short v[86:87], v64, off
	v_add_u32_e32 v64, 33, v138
	v_add_u32_e32 v82, 40, v138
	s_waitcnt lgkmcnt(0)
	v_add_f32_e32 v81, v65, v112
	v_ashrrev_i32_e32 v65, 31, v64
	v_lshl_add_u64 v[64:65], s[16:17], 0, v[64:65]
	v_lshlrev_b64 v[64:65], 12, v[64:65]
	v_mul_f32_e32 v81, v81, v83
	v_lshl_add_u64 v[64:65], s[26:27], 0, v[64:65]
	v_cvt_pk_bf16_f32 v81, v81, s0
	v_lshl_add_u64 v[64:65], v[64:65], 0, v[136:137]
	global_store_short v[64:65], v81, off
	v_add_u32_e32 v64, 34, v138
	v_ashrrev_i32_e32 v83, 31, v82
	s_waitcnt lgkmcnt(0)
	v_add_f32_e32 v66, v66, v113
	v_ashrrev_i32_e32 v65, 31, v64
	v_lshl_add_u64 v[64:65], s[16:17], 0, v[64:65]
	v_lshlrev_b64 v[64:65], 12, v[64:65]
	v_mul_f32_e32 v66, v66, v84
	v_lshl_add_u64 v[64:65], s[26:27], 0, v[64:65]
	v_cvt_pk_bf16_f32 v66, v66, s0
	v_lshl_add_u64 v[64:65], v[64:65], 0, v[136:137]
	global_store_short v[64:65], v66, off
	v_add_u32_e32 v64, 35, v138
	s_waitcnt lgkmcnt(0)
	v_add_f32_e32 v66, v67, v114
	v_ashrrev_i32_e32 v65, 31, v64
	v_lshl_add_u64 v[64:65], s[16:17], 0, v[64:65]
	v_lshlrev_b64 v[64:65], 12, v[64:65]
	v_mul_f32_e32 v66, v66, v85
	v_lshl_add_u64 v[64:65], s[26:27], 0, v[64:65]
	v_cvt_pk_bf16_f32 v66, v66, s0
	v_lshl_add_u64 v[64:65], v[64:65], 0, v[136:137]
	global_store_short v[64:65], v66, off
	v_lshl_add_u64 v[82:83], s[16:17], 0, v[82:83]
	v_lshlrev_b64 v[82:83], 12, v[82:83]
	v_lshl_add_u64 v[82:83], s[26:27], 0, v[82:83]
	v_lshl_add_u64 v[82:83], v[82:83], 0, v[136:137]
	s_waitcnt lgkmcnt(0)
	v_add_f32_e32 v68, v68, v115
	ds_read_b128 v[64:67], v80 offset:160
	s_waitcnt lgkmcnt(0)
	v_mul_f32_e32 v64, v68, v64
	v_cvt_pk_bf16_f32 v64, v64, s0
	v_add_u32_e32 v68, 41, v138
	global_store_short v[82:83], v64, off
	s_waitcnt lgkmcnt(0)
; DI int crow(int reg, int h) { return (reg & 3) + 8 * (reg >> 2) + 4 * h; }
; DI void mlstm_item(const float* b_i, const float* b_f, const bf16_t* proj, const bf16_t* Hqk, bf16_t* mix, int item, LP unsigned char* lds3) {
;     ...
;         for (int i = 0; i < 16; ++i) { const int t = ti * 32 + crow(i, hh);
;           mix[(tok0 + t) * 2048 + h * 512 + vq * 128 + vi * 32 + r] = f2bf((acc[ti][i] + X[t * 128 + vi * 32 + r]) * qn[t]); }
	v_add_f32_e32 v64, v69, v116
	v_ashrrev_i32_e32 v69, 31, v68
	v_mul_f32_e32 v64, v64, v65
	v_cvt_pk_bf16_f32 v81, v64, s0
	v_lshl_add_u64 v[64:65], s[16:17], 0, v[68:69]
	v_lshlrev_b64 v[64:65], 12, v[64:65]
	v_lshl_add_u64 v[64:65], s[26:27], 0, v[64:65]
	v_lshl_add_u64 v[64:65], v[64:65], 0, v[136:137]
	global_store_short v[64:65], v81, off
	v_add_u32_e32 v64, 42, v138
	s_waitcnt lgkmcnt(0)
	v_add_f32_e32 v68, v70, v117
	v_ashrrev_i32_e32 v65, 31, v64
	v_lshl_add_u64 v[64:65], s[16:17], 0, v[64:65]
	v_lshlrev_b64 v[64:65], 12, v[64:65]
	v_mul_f32_e32 v66, v68, v66
	v_lshl_add_u64 v[64:65], s[26:27], 0, v[64:65]
	v_cvt_pk_bf16_f32 v66, v66, s0
	v_lshl_add_u64 v[64:65], v[64:65], 0, v[136:137]
	global_store_short v[64:65], v66, off
	v_add_u32_e32 v64, 43, v138
	v_add_u32_e32 v68, 48, v138
	v_ashrrev_i32_e32 v69, 31, v68
	s_waitcnt lgkmcnt(0)
	v_add_f32_e32 v66, v71, v118
	v_ashrrev_i32_e32 v65, 31, v64
	v_lshl_add_u64 v[64:65], s[16:17], 0, v[64:65]
	v_lshlrev_b64 v[64:65], 12, v[64:65]
	v_mul_f32_e32 v66, v66, v67
	v_lshl_add_u64 v[64:65], s[26:27], 0, v[64:65]
	v_cvt_pk_bf16_f32 v66, v66, s0
	v_lshl_add_u64 v[64:65], v[64:65], 0, v[136:137]
	global_store_short v[64:65], v66, off
	v_lshl_add_u64 v[68:69], s[16:17], 0, v[68:69]
	v_lshlrev_b64 v[68:69], 12, v[68:69]
	v_lshl_add_u64 v[68:69], s[26:27], 0, v[68:69]
	v_lshl_add_u64 v[68:69], v[68:69], 0, v[136:137]
	s_waitcnt lgkmcnt(0)
	v_add_f32_e32 v70, v72, v119
	ds_read_b128 v[64:67], v80 offset:192
	s_waitcnt lgkmcnt(0)
	v_mul_f32_e32 v64, v70, v64
	v_cvt_pk_bf16_f32 v64, v64, s0
	global_store_short v[68:69], v64, off
	v_add_u32_e32 v68, 49, v138
	v_ashrrev_i32_e32 v69, 31, v68
	s_waitcnt lgkmcnt(0)
	v_add_f32_e32 v64, v73, v120
	v_mul_f32_e32 v64, v64, v65
	v_cvt_pk_bf16_f32 v70, v64, s0
	v_lshl_add_u64 v[64:65], s[16:17], 0, v[68:69]
	v_lshlrev_b64 v[64:65], 12, v[64:65]
	v_lshl_add_u64 v[64:65], s[26:27], 0, v[64:65]
	v_lshl_add_u64 v[64:65], v[64:65], 0, v[136:137]
	global_store_short v[64:65], v70, off
	v_add_u32_e32 v64, 50, v138
	s_waitcnt lgkmcnt(0)
	v_add_f32_e32 v68, v74, v121
	v_ashrrev_i32_e32 v65, 31, v64
	v_lshl_add_u64 v[64:65], s[16:17], 0, v[64:65]
	v_lshlrev_b64 v[64:65], 12, v[64:65]
	v_mul_f32_e32 v66, v68, v66
	v_lshl_add_u64 v[64:65], s[26:27], 0, v[64:65]
	v_cvt_pk_bf16_f32 v66, v66, s0
	v_lshl_add_u64 v[64:65], v[64:65], 0, v[136:137]
	global_store_short v[64:65], v66, off
	v_add_u32_e32 v64, 51, v138
	v_add_u32_e32 v68, 56, v138
	v_ashrrev_i32_e32 v69, 31, v68
	s_waitcnt lgkmcnt(0)
	v_add_f32_e32 v66, v75, v122
	v_ashrrev_i32_e32 v65, 31, v64
	v_lshl_add_u64 v[64:65], s[16:17], 0, v[64:65]
	v_lshlrev_b64 v[64:65], 12, v[64:65]
	v_mul_f32_e32 v66, v66, v67
	v_lshl_add_u64 v[64:65], s[26:27], 0, v[64:65]
	v_cvt_pk_bf16_f32 v66, v66, s0
	v_lshl_add_u64 v[64:65], v[64:65], 0, v[136:137]
	global_store_short v[64:65], v66, off
	v_lshl_add_u64 v[68:69], s[16:17], 0, v[68:69]
	v_lshlrev_b64 v[68:69], 12, v[68:69]
	v_lshl_add_u64 v[68:69], s[26:27], 0, v[68:69]
	v_lshl_add_u64 v[68:69], v[68:69], 0, v[136:137]
	s_waitcnt lgkmcnt(0)
	v_add_f32_e32 v70, v76, v123
	ds_read_b128 v[64:67], v80 offset:224
	s_waitcnt lgkmcnt(0)
	v_mul_f32_e32 v64, v70, v64
	v_cvt_pk_bf16_f32 v64, v64, s0
	global_store_short v[68:69], v64, off
	v_add_u32_e32 v68, 57, v138
	v_ashrrev_i32_e32 v69, 31, v68
	s_waitcnt lgkmcnt(0)
	v_add_f32_e32 v64, v77, v124
	v_mul_f32_e32 v64, v64, v65
	v_cvt_pk_bf16_f32 v70, v64, s0
	v_lshl_add_u64 v[64:65], s[16:17], 0, v[68:69]
	v_lshlrev_b64 v[64:65], 12, v[64:65]
	v_lshl_add_u64 v[64:65], s[26:27], 0, v[64:65]
	v_lshl_add_u64 v[64:65], v[64:65], 0, v[136:137]
	global_store_short v[64:65], v70, off
	v_add_u32_e32 v64, 58, v138
	s_waitcnt lgkmcnt(0)
	v_add_f32_e32 v68, v78, v125
	v_ashrrev_i32_e32 v65, 31, v64
	v_lshl_add_u64 v[64:65], s[16:17], 0, v[64:65]
	v_lshlrev_b64 v[64:65], 12, v[64:65]
	v_mul_f32_e32 v66, v68, v66
	v_lshl_add_u64 v[64:65], s[26:27], 0, v[64:65]
	v_cvt_pk_bf16_f32 v66, v66, s0
	v_lshl_add_u64 v[64:65], v[64:65], 0, v[136:137]
	global_store_short v[64:65], v66, off
	v_add_u32_e32 v64, 59, v138
	s_waitcnt lgkmcnt(0)
	v_add_f32_e32 v66, v79, v126
	v_ashrrev_i32_e32 v65, 31, v64
	v_lshl_add_u64 v[64:65], s[16:17], 0, v[64:65]
	v_lshlrev_b64 v[64:65], 12, v[64:65]
	v_mul_f32_e32 v66, v66, v67
	v_lshl_add_u64 v[64:65], s[26:27], 0, v[64:65]
	v_cvt_pk_bf16_f32 v66, v66, s0
	v_lshl_add_u64 v[64:65], v[64:65], 0, v[136:137]
	global_store_short v[64:65], v66, off

; #define MFMA32(a, b, c) __builtin_amdgcn_mfma_f32_32x32x16_bf16((a), (b), (c), 0, 0, 0)
; DI void mma_tile(f32x16& acc, const bf16_t* A, int lda, const bf16_t* Bt, int ldb, int K, int lane) {
;   const int r = lane & 31, h = lane >> 5;
;   const bf16_t* ap = A + r * lda + 8 * h; const bf16_t* bp = Bt + r * ldb + 8 * h;
; #pragma unroll 2
;   for (int k = 0; k < K; k += 16) acc = MFMA32(*(const bf16x8*)(ap + k), *(const bf16x8*)(bp + k), acc);
; DI void mlstm_item(const float* b_i, const float* b_f, const bf16_t* proj, const bf16_t* Hqk, bf16_t* mix, int item, LP unsigned char* lds3) {
;     ...
;     { const float dc = scal[1];
; #pragma unroll
;       for (int jj = 0; jj < 4; ++jj) {
; #pragma unroll
;         for (int i = 0; i < 16; ++i) cst[jj][i] *= dc;
;         mma_tile(cst[jj], KwT + (dh * 4 + jj) * 32 * 72, 72, VT + vi * 32 * 72, 72, 64, lane); } }
.LBB0_227:
	ds_read_b128 v[70:73], v68
	v_subrev_u32_e32 v74, 32, v69
	ds_read_b128 v[74:77], v74
	ds_read_b128 v[136:139], v68 offset:32
	ds_read_b128 v[140:143], v69
	s_waitcnt lgkmcnt(2)
	v_mfma_f32_32x32x16_bf16 v[48:63], v[70:73], v[74:77], v[48:63]
	ds_read_b128 v[70:73], v68 offset:64
	ds_read_b128 v[74:77], v69 offset:32
	s_waitcnt lgkmcnt(2)
	v_mfma_f32_32x32x16_bf16 v[48:63], v[136:139], v[140:143], v[48:63]
	ds_read_b128 v[136:139], v68 offset:96
	ds_read_b128 v[140:143], v69 offset:64
	s_waitcnt lgkmcnt(2)
	v_mfma_f32_32x32x16_bf16 v[48:63], v[70:73], v[74:77], v[48:63]
	s_waitcnt lgkmcnt(0)
	v_mfma_f32_32x32x16_bf16 v[48:63], v[136:139], v[140:143], v[48:63]
	v_add_u32_e32 v69, 0x80, v69
	v_add_u32_e32 v68, 0x80, v68
	s_add_i32 s4, s4, 64
	s_cmp_lt_u32 s4, 48
	v_mov_b32_e32 v68, v64
	v_mov_b32_e32 v69, v64
	v_pk_mul_f32 v[46:47], v[46:47], v[68:69]
	v_pk_mul_f32 v[44:45], v[44:45], v[68:69]
	v_pk_mul_f32 v[42:43], v[42:43], v[68:69]
	v_pk_mul_f32 v[40:41], v[40:41], v[68:69]
	v_pk_mul_f32 v[38:39], v[38:39], v[68:69]
	v_pk_mul_f32 v[36:37], v[36:37], v[68:69]
	v_pk_mul_f32 v[34:35], v[34:35], v[68:69]
	v_pk_mul_f32 v[32:33], v[32:33], v[64:65]
	v_add_u32_e32 v68, v238, v67
	s_mov_b32 s4, -16
	v_mov_b32_e32 v69, v66
.LBB0_229:
	ds_read_b128 v[70:73], v68
	v_subrev_u32_e32 v74, 32, v69
	ds_read_b128 v[74:77], v74
	ds_read_b128 v[136:139], v68 offset:32
	ds_read_b128 v[140:143], v69
	s_waitcnt lgkmcnt(2)
	v_mfma_f32_32x32x16_bf16 v[32:47], v[70:73], v[74:77], v[32:47]
	ds_read_b128 v[70:73], v68 offset:64
	ds_read_b128 v[74:77], v69 offset:32
	s_waitcnt lgkmcnt(2)
	v_mfma_f32_32x32x16_bf16 v[32:47], v[136:139], v[140:143], v[32:47]
	ds_read_b128 v[136:139], v68 offset:96
	ds_read_b128 v[140:143], v69 offset:64
	s_waitcnt lgkmcnt(2)
	v_mfma_f32_32x32x16_bf16 v[32:47], v[70:73], v[74:77], v[32:47]
	s_waitcnt lgkmcnt(0)
	v_mfma_f32_32x32x16_bf16 v[32:47], v[136:139], v[140:143], v[32:47]
	v_add_u32_e32 v69, 0x80, v69
	v_add_u32_e32 v68, 0x80, v68
	s_add_i32 s4, s4, 64
	s_cmp_lt_u32 s4, 48
	v_mov_b32_e32 v68, v64
	v_mov_b32_e32 v69, v64
	v_pk_mul_f32 v[30:31], v[30:31], v[68:69]
	v_pk_mul_f32 v[28:29], v[28:29], v[68:69]
	v_pk_mul_f32 v[26:27], v[26:27], v[68:69]
	v_pk_mul_f32 v[24:25], v[24:25], v[68:69]
	v_pk_mul_f32 v[22:23], v[22:23], v[68:69]
	v_pk_mul_f32 v[20:21], v[20:21], v[68:69]
	v_pk_mul_f32 v[18:19], v[18:19], v[68:69]
	v_pk_mul_f32 v[16:17], v[16:17], v[64:65]
	v_add_u32_e32 v68, v239, v67
	s_mov_b32 s4, -16
	v_mov_b32_e32 v69, v66
.LBB0_231:
	ds_read_b128 v[70:73], v68
	v_subrev_u32_e32 v74, 32, v69
	ds_read_b128 v[74:77], v74
	ds_read_b128 v[136:139], v68 offset:32
	ds_read_b128 v[140:143], v69
	s_waitcnt lgkmcnt(2)
	v_mfma_f32_32x32x16_bf16 v[16:31], v[70:73], v[74:77], v[16:31]
	ds_read_b128 v[70:73], v68 offset:64
	ds_read_b128 v[74:77], v69 offset:32
	s_waitcnt lgkmcnt(2)
	v_mfma_f32_32x32x16_bf16 v[16:31], v[136:139], v[140:143], v[16:31]
	ds_read_b128 v[136:139], v68 offset:96
	ds_read_b128 v[140:143], v69 offset:64
	s_waitcnt lgkmcnt(2)
	v_mfma_f32_32x32x16_bf16 v[16:31], v[70:73], v[74:77], v[16:31]
	s_waitcnt lgkmcnt(0)
	v_mfma_f32_32x32x16_bf16 v[16:31], v[136:139], v[140:143], v[16:31]
	v_add_u32_e32 v69, 0x80, v69
	v_add_u32_e32 v68, 0x80, v68
	s_add_i32 s4, s4, 64
	s_cmp_lt_u32 s4, 48
	v_mov_b32_e32 v68, v64
	v_mov_b32_e32 v69, v64
	v_pk_mul_f32 v[14:15], v[14:15], v[68:69]
	v_pk_mul_f32 v[12:13], v[12:13], v[68:69]
	v_pk_mul_f32 v[10:11], v[10:11], v[68:69]
	v_pk_mul_f32 v[8:9], v[8:9], v[68:69]
	v_pk_mul_f32 v[6:7], v[6:7], v[68:69]
	v_pk_mul_f32 v[4:5], v[4:5], v[68:69]
	v_pk_mul_f32 v[2:3], v[2:3], v[68:69]
	v_pk_mul_f32 v[0:1], v[0:1], v[64:65]
	v_add_u32_e32 v64, v240, v67
	s_mov_b32 s4, -16
.LBB0_233:
	ds_read_b128 v[68:71], v64
	v_subrev_u32_e32 v65, 32, v66
	ds_read_b128 v[72:75], v65
	ds_read_b128 v[136:139], v64 offset:32
	ds_read_b128 v[140:143], v66
	s_waitcnt lgkmcnt(2)
	v_mfma_f32_32x32x16_bf16 v[0:15], v[68:71], v[72:75], v[0:15]
	ds_read_b128 v[68:71], v64 offset:64
	ds_read_b128 v[72:75], v66 offset:32
	s_waitcnt lgkmcnt(2)
	v_mfma_f32_32x32x16_bf16 v[0:15], v[136:139], v[140:143], v[0:15]
	ds_read_b128 v[136:139], v64 offset:96
	ds_read_b128 v[140:143], v66 offset:64
	s_waitcnt lgkmcnt(2)
	v_mfma_f32_32x32x16_bf16 v[0:15], v[68:71], v[72:75], v[0:15]
	s_waitcnt lgkmcnt(0)
	v_mfma_f32_32x32x16_bf16 v[0:15], v[136:139], v[140:143], v[0:15]
	v_add_u32_e32 v66, 0x80, v66
	v_add_u32_e32 v64, 0x80, v64
	s_add_i32 s4, s4, 64
	s_cmp_lt_u32 s4, 48
	s_add_i32 s46, s46, 1
	s_cmp_lg_u32 s46, 32
	s_barrier
	s_cbranch_scc1 .LBB0_159
	s_add_i32 s35, s35, s34
	s_cmpk_gt_i32 s35, 0xff
	s_cbranch_scc0 .LBB0_152
